# LayerNorm row loops: loop-invariant gamma/beta loaded once before the loop (8 loads and 4 serialized waits per row removed); bit-identical
# speedup vs baseline: 1.0107x; 1.0031x over previous
.LBB0_296:
	v_lshrrev_b32_e32 v0, 6, v154
	v_lshl_add_u32 v8, s2, 2, v0
	s_movk_i32 s3, 0x4000
	v_cmp_gt_i32_e32 vcc, s3, v8
	s_and_saveexec_b64 s[4:5], vcc
	s_cbranch_execz .LBB0_299
	v_mbcnt_lo_u32_b32 v0, -1, 0
	v_mbcnt_hi_u32_b32 v0, -1, v0
	v_and_b32_e32 v1, 64, v0
	v_add_u32_e32 v1, 64, v1
	v_xor_b32_e32 v2, 32, v0
	v_cmp_lt_i32_e32 vcc, v2, v1
	v_readlane_b32 s8, v245, 5
	v_readlane_b32 s9, v245, 6
	v_cndmask_b32_e32 v2, v0, v2, vcc
	v_lshlrev_b32_e32 v22, 2, v2
	v_xor_b32_e32 v2, 16, v0
	v_cmp_lt_i32_e32 vcc, v2, v1
	v_readlane_b32 s10, v245, 7
	v_readlane_b32 s11, v245, 8
	v_cndmask_b32_e32 v2, v0, v2, vcc
	v_lshlrev_b32_e32 v23, 2, v2
	v_xor_b32_e32 v2, 8, v0
	v_cmp_lt_i32_e32 vcc, v2, v1
	v_readlane_b32 s12, v245, 9
	v_readlane_b32 s13, v245, 10
	v_cndmask_b32_e32 v2, v0, v2, vcc
	v_lshlrev_b32_e32 v24, 2, v2
	v_xor_b32_e32 v2, 4, v0
	v_cmp_lt_i32_e32 vcc, v2, v1
	v_readlane_b32 s14, v245, 11
	v_readlane_b32 s15, v245, 12
	v_cndmask_b32_e32 v2, v0, v2, vcc
	v_lshlrev_b32_e32 v25, 2, v2
	v_xor_b32_e32 v2, 2, v0
	v_cmp_lt_i32_e32 vcc, v2, v1
	v_readlane_b32 s16, v245, 13
	v_readlane_b32 s17, v245, 14
	v_cndmask_b32_e32 v2, v0, v2, vcc
	v_lshlrev_b32_e32 v26, 2, v2
	v_xor_b32_e32 v2, 1, v0
	v_cmp_lt_i32_e32 vcc, v2, v1
	v_readlane_b32 s18, v245, 15
	v_readlane_b32 s19, v245, 16
	v_cndmask_b32_e32 v0, v0, v2, vcc
	v_lshlrev_b32_e32 v27, 2, v0
	v_lshlrev_b32_e32 v0, 4, v154
	v_readlane_b32 s20, v245, 17
	v_readlane_b32 s21, v245, 18
	v_readlane_b32 s22, v245, 19
	v_readlane_b32 s23, v245, 20
	v_ashrrev_i32_e32 v9, 31, v8
	v_and_b32_e32 v10, 0x3f0, v0
	v_mov_b32_e32 v11, 0
	s_mov_b64 s[6:7], s[10:11]
	s_mov_b64 s[8:9], s[12:13]
	v_and_b32_e32 v4, 63, v154
	v_lshlrev_b64 v[2:3], 11, v[8:9]
	v_readlane_b32 s12, v245, 37
	v_lshl_add_u64 v[12:13], s[6:7], 0, v[10:11]
	s_lshl_b32 s6, s33, 2
	v_lshl_or_b32 v2, v4, 3, v2
	v_readlane_b32 s24, v245, 49
	v_readlane_b32 s25, v245, 50
	v_lshlrev_b64 v[0:1], 12, v[8:9]
	s_ashr_i32 s7, s6, 31
	v_readlane_b32 s13, v245, 38
	v_lshl_add_u64 v[2:3], s[24:25], 0, v[2:3]
	s_mov_b64 s[10:11], 0x400
	v_lshl_add_u64 v[14:15], s[8:9], 0, v[10:11]
	v_lshlrev_b32_e32 v10, 4, v4
	v_lshl_add_u64 v[16:17], s[38:39], 0, v[0:1]
	s_lshl_b64 s[8:9], s[6:7], 12
	v_lshl_add_u64 v[18:19], v[2:3], 0, s[10:11]
	s_lshl_b64 s[10:11], s[6:7], 11
	v_lshl_add_u64 v[20:21], s[40:41], 0, v[0:1]
	s_mov_b64 s[12:13], 0
	v_mov_b32_e32 v9, 0x3727c5ac
	s_mov_b32 s3, 0x800000
	s_movk_i32 s7, 0x3fff
	v_readlane_b32 s14, v245, 39
	v_readlane_b32 s15, v245, 40
	v_readlane_b32 s16, v245, 41
	v_readlane_b32 s17, v245, 42
	v_readlane_b32 s18, v245, 43
	v_readlane_b32 s19, v245, 44
	v_readlane_b32 s20, v245, 45
	v_readlane_b32 s21, v245, 46
	v_readlane_b32 s22, v245, 47
	v_readlane_b32 s23, v245, 48
	v_readlane_b32 s26, v245, 51
	v_readlane_b32 s27, v245, 52
	global_load_dwordx4 v[200:203], v[12:13], off
	global_load_dwordx4 v[216:219], v[14:15], off
	global_load_dwordx4 v[204:207], v[12:13], off offset:1024
	global_load_dwordx4 v[220:223], v[14:15], off offset:1024
	global_load_dwordx4 v[208:211], v[12:13], off offset:2048
	global_load_dwordx4 v[224:227], v[14:15], off offset:2048
	global_load_dwordx4 v[212:215], v[12:13], off offset:3072
	global_load_dwordx4 v[228:231], v[14:15], off offset:3072
.LBB0_298:
	v_lshl_add_u64 v[0:1], v[16:17], 0, v[10:11]
	global_load_dwordx4 v[28:31], v[0:1], off
	global_load_dwordx4 v[32:35], v[0:1], off offset:1024
	global_load_dwordx4 v[4:7], v[0:1], off offset:2048
	s_nop 0
	global_load_dwordx4 v[0:3], v[0:1], off offset:3072
	s_nop 0
	v_lshl_add_u64 v[44:45], v[20:21], 0, v[10:11]
	v_add_u32_e32 v8, s6, v8
	v_lshl_add_u64 v[16:17], v[16:17], 0, s[8:9]
	v_lshl_add_u64 v[20:21], v[20:21], 0, s[8:9]
	s_waitcnt vmcnt(3)
	v_mov_b32_e32 v46, v29
	v_mov_b32_e32 v47, v30
	v_mov_b32_e32 v48, v28
	v_mov_b32_e32 v49, v31
	s_waitcnt vmcnt(2)
	v_mov_b32_e32 v50, v33
	v_mov_b32_e32 v51, v34
	v_mov_b32_e32 v52, v32
	v_mov_b32_e32 v53, v35
	v_pk_add_f32 v[46:47], v[46:47], v[48:49]
	v_pk_add_f32 v[48:49], v[50:51], v[52:53]
	v_add_f32_e32 v52, v46, v47
	v_pk_add_f32 v[46:47], v[48:49], v[48:49] op_sel:[0,1] op_sel_hi:[1,0]
	s_waitcnt vmcnt(1)
	v_add_f32_e32 v54, v4, v5
	v_add_f32_e32 v56, v6, v7
	s_waitcnt vmcnt(0)
	v_mov_b32_e32 v59, v0
	v_mov_b32_e32 v55, v2
	v_mov_b32_e32 v57, v3
	v_add_f32_e32 v58, 0, v52
	v_mov_b32_e32 v47, v1
	v_pk_add_f32 v[50:51], v[54:55], v[56:57]
	v_pk_add_f32 v[46:47], v[58:59], v[46:47]
	s_nop 0
	v_pk_add_f32 v[46:47], v[46:47], v[50:51]
	s_nop 0
	v_add_f32_e32 v46, v46, v47
	ds_bpermute_b32 v47, v22, v46
	s_waitcnt lgkmcnt(0)
	v_add_f32_e32 v46, v46, v47
	ds_bpermute_b32 v47, v23, v46
	s_waitcnt lgkmcnt(0)
	v_add_f32_e32 v46, v46, v47
	ds_bpermute_b32 v47, v24, v46
	s_waitcnt lgkmcnt(0)
	v_add_f32_e32 v46, v46, v47
	ds_bpermute_b32 v47, v25, v46
	s_waitcnt lgkmcnt(0)
	v_add_f32_e32 v46, v46, v47
	ds_bpermute_b32 v47, v26, v46
	s_waitcnt lgkmcnt(0)
	v_add_f32_e32 v46, v46, v47
	ds_bpermute_b32 v47, v27, v46
	s_waitcnt lgkmcnt(0)
	v_add_f32_e32 v50, v46, v47
	v_fmamk_f32 v29, v50, 0xba800000, v29
	v_fmamk_f32 v28, v50, 0xba800000, v28
	v_fmamk_f32 v31, v50, 0xba800000, v31
	v_fmac_f32_e32 v30, 0xba800000, v50
	v_fmamk_f32 v33, v50, 0xba800000, v33
	v_fmamk_f32 v32, v50, 0xba800000, v32
	v_fmamk_f32 v35, v50, 0xba800000, v35
	v_fmac_f32_e32 v34, 0xba800000, v50
	v_fmamk_f32 v47, v50, 0xba800000, v5
	v_fmamk_f32 v46, v50, 0xba800000, v4
	v_fmamk_f32 v7, v50, 0xba800000, v7
	v_fmac_f32_e32 v6, 0xba800000, v50
	v_fmamk_f32 v49, v50, 0xba800000, v3
	v_fmamk_f32 v48, v50, 0xba800000, v2
	v_fmamk_f32 v1, v50, 0xba800000, v1
	v_fmac_f32_e32 v0, 0xba800000, v50
	v_pk_mul_f32 v[2:3], v[30:31], v[30:31]
	v_pk_mul_f32 v[4:5], v[28:29], v[28:29]
	v_pk_mul_f32 v[50:51], v[34:35], v[34:35]
	v_pk_mul_f32 v[52:53], v[32:33], v[32:33]
	v_pk_mov_b32 v[58:59], v[4:5], v[2:3] op_sel:[1,0]
	v_mov_b32_e32 v5, v3
	v_pk_mov_b32 v[2:3], v[52:53], v[50:51] op_sel:[1,0]
	v_mov_b32_e32 v53, v51
	v_mul_f32_e32 v54, v46, v46
	v_mul_f32_e32 v56, v6, v6
	v_pk_add_f32 v[4:5], v[58:59], v[4:5]
	v_pk_add_f32 v[2:3], v[2:3], v[52:53]
	v_pk_fma_f32 v[50:51], v[46:47], v[46:47], v[54:55] op_sel_hi:[1,1,0]
	v_pk_fma_f32 v[54:55], v[6:7], v[6:7], v[56:57] op_sel_hi:[1,1,0]
	v_pk_add_f32 v[4:5], v[4:5], v[4:5] op_sel_hi:[0,1]
	v_pk_add_f32 v[2:3], v[2:3], v[2:3] op_sel_hi:[0,1]
	v_mul_f32_e32 v50, v0, v0
	v_mul_f32_e32 v54, v1, v1
	v_mul_f32_e32 v4, v48, v48
	v_mul_f32_e32 v2, v49, v49
	v_pk_add_f32 v[50:51], v[50:51], v[54:55]
	v_pk_add_f32 v[2:3], v[4:5], v[2:3]
	s_nop 0
	v_pk_add_f32 v[2:3], v[50:51], v[2:3]
	s_nop 0
	v_add_f32_e32 v2, v2, v3
	ds_bpermute_b32 v3, v22, v2
	s_waitcnt lgkmcnt(0)
	v_add_f32_e32 v2, v2, v3
	ds_bpermute_b32 v3, v23, v2
	s_waitcnt lgkmcnt(0)
	v_add_f32_e32 v2, v2, v3
	ds_bpermute_b32 v3, v24, v2
	s_waitcnt lgkmcnt(0)
	v_add_f32_e32 v2, v2, v3
	ds_bpermute_b32 v3, v25, v2
	s_waitcnt lgkmcnt(0)
	v_add_f32_e32 v2, v2, v3
	ds_bpermute_b32 v3, v26, v2
	s_waitcnt lgkmcnt(0)
	v_add_f32_e32 v2, v2, v3
	ds_bpermute_b32 v3, v27, v2
	s_waitcnt lgkmcnt(0)
	v_add_f32_e32 v2, v2, v3
	v_fmamk_f32 v2, v2, 0x3a800000, v9
	v_mul_f32_e32 v3, 0x4b800000, v2
	v_cmp_gt_f32_e32 vcc, s3, v2
	s_nop 1
	v_cndmask_b32_e32 v2, v2, v3, vcc
	v_rsq_f32_e32 v2, v2
	s_nop 0
	v_mul_f32_e32 v3, 0x45800000, v2
	v_cndmask_b32_e32 v50, v2, v3, vcc
	v_pk_mul_f32 v[2:3], v[28:29], v[50:51] op_sel_hi:[1,0]
	v_pk_mul_f32 v[4:5], v[30:31], v[50:51] op_sel_hi:[1,0]
	s_nop 1
	v_pk_fma_f32 v[2:3], v[200:201], v[2:3], v[216:217]
	v_pk_fma_f32 v[4:5], v[202:203], v[4:5], v[218:219]
	global_store_dwordx4 v[44:45], v[2:5], off
	v_pk_mul_f32 v[34:35], v[34:35], v[50:51] op_sel_hi:[1,0]
	v_pk_mul_f32 v[32:33], v[32:33], v[50:51] op_sel_hi:[1,0]
	v_cvt_pk_bf16_f32 v2, v2, v3
	v_cvt_pk_bf16_f32 v3, v4, v5
	global_store_dwordx2 v[18:19], v[2:3], off offset:-1024
	s_nop 0
	v_pk_mul_f32 v[6:7], v[6:7], v[50:51] op_sel_hi:[1,0]
	v_pk_mul_f32 v[0:1], v[0:1], v[50:51] op_sel_hi:[1,0]
	v_cmp_lt_i32_e32 vcc, s7, v8
	s_or_b64 s[12:13], vcc, s[12:13]
	s_nop 1
	v_pk_fma_f32 v[2:3], v[204:205], v[32:33], v[220:221]
	v_pk_fma_f32 v[4:5], v[206:207], v[34:35], v[222:223]
	global_store_dwordx4 v[44:45], v[2:5], off offset:1024
	v_pk_mul_f32 v[32:33], v[46:47], v[50:51] op_sel_hi:[1,0]
	s_nop 0
	v_cvt_pk_bf16_f32 v2, v2, v3
	v_cvt_pk_bf16_f32 v3, v4, v5
	global_store_dwordx2 v[18:19], v[2:3], off offset:-512
	s_nop 0
	s_nop 1
	v_pk_fma_f32 v[2:3], v[208:209], v[32:33], v[224:225]
	v_pk_fma_f32 v[4:5], v[210:211], v[6:7], v[226:227]
	global_store_dwordx4 v[44:45], v[2:5], off offset:2048
	v_pk_mul_f32 v[6:7], v[48:49], v[50:51] op_sel_hi:[1,0]
	s_nop 0
	v_cvt_pk_bf16_f32 v2, v2, v3
	v_cvt_pk_bf16_f32 v3, v4, v5
	global_store_dwordx2 v[18:19], v[2:3], off
	s_nop 0
	s_nop 1
	v_pk_fma_f32 v[0:1], v[212:213], v[0:1], v[228:229]
	v_pk_fma_f32 v[2:3], v[214:215], v[6:7], v[230:231]
	global_store_dwordx4 v[44:45], v[0:3], off offset:3072
	s_nop 1
	v_cvt_pk_bf16_f32 v0, v0, v1
	v_cvt_pk_bf16_f32 v1, v2, v3
	global_store_dwordx2 v[18:19], v[0:1], off offset:512
	v_lshl_add_u64 v[18:19], v[18:19], 0, s[10:11]
	s_andn2_b64 exec, exec, s[12:13]
	s_cbranch_execnz .LBB0_298

.LBB0_605:
	v_lshrrev_b32_e32 v0, 6, v154
	v_lshl_add_u32 v8, s2, 2, v0
	s_movk_i32 s0, 0x4000
	v_cmp_gt_i32_e32 vcc, s0, v8
	s_and_saveexec_b64 s[0:1], vcc
	s_cbranch_execz .LBB0_608
	v_mbcnt_lo_u32_b32 v0, -1, 0
	v_mbcnt_hi_u32_b32 v0, -1, v0
	v_and_b32_e32 v1, 64, v0
	v_add_u32_e32 v1, 64, v1
	v_xor_b32_e32 v2, 32, v0
	v_cmp_lt_i32_e32 vcc, v2, v1
	v_readlane_b32 s8, v245, 5
	v_readlane_b32 s10, v245, 7
	v_cndmask_b32_e32 v2, v0, v2, vcc
	v_lshlrev_b32_e32 v22, 2, v2
	v_xor_b32_e32 v2, 16, v0
	v_cmp_lt_i32_e32 vcc, v2, v1
	v_readlane_b32 s11, v245, 8
	v_mov_b32_e32 v11, 0
	v_cndmask_b32_e32 v2, v0, v2, vcc
	v_lshlrev_b32_e32 v23, 2, v2
	v_xor_b32_e32 v2, 8, v0
	v_cmp_lt_i32_e32 vcc, v2, v1
	v_readlane_b32 s9, v245, 6
	v_readlane_b32 s12, v245, 9
	v_cndmask_b32_e32 v2, v0, v2, vcc
	v_lshlrev_b32_e32 v24, 2, v2
	v_xor_b32_e32 v2, 4, v0
	v_cmp_lt_i32_e32 vcc, v2, v1
	v_readlane_b32 s13, v245, 10
	s_mov_b64 s[6:7], s[10:11]
	v_cndmask_b32_e32 v2, v0, v2, vcc
	v_lshlrev_b32_e32 v25, 2, v2
	v_xor_b32_e32 v2, 2, v0
	v_cmp_lt_i32_e32 vcc, v2, v1
	v_readlane_b32 s14, v245, 11
	v_readlane_b32 s15, v245, 12
	v_cndmask_b32_e32 v2, v0, v2, vcc
	v_lshlrev_b32_e32 v26, 2, v2
	v_xor_b32_e32 v2, 1, v0
	v_cmp_lt_i32_e32 vcc, v2, v1
	v_readlane_b32 s16, v245, 13
	v_readlane_b32 s17, v245, 14
	v_cndmask_b32_e32 v0, v0, v2, vcc
	v_lshlrev_b32_e32 v27, 2, v0
	v_lshlrev_b32_e32 v0, 4, v154
	v_and_b32_e32 v10, 0x3f0, v0
	v_readlane_b32 s18, v245, 15
	v_readlane_b32 s19, v245, 16
	v_readlane_b32 s20, v245, 17
	v_readlane_b32 s21, v245, 18
	v_readlane_b32 s22, v245, 19
	v_readlane_b32 s23, v245, 20
	s_mov_b64 s[8:9], s[12:13]
	v_lshl_add_u64 v[0:1], s[6:7], 0, v[10:11]
	s_mov_b64 s[6:7], 0x2000
	v_ashrrev_i32_e32 v9, 31, v8
	v_lshl_add_u64 v[12:13], v[0:1], 0, s[6:7]
	v_lshl_add_u64 v[0:1], s[8:9], 0, v[10:11]
	v_and_b32_e32 v4, 63, v154
	v_lshlrev_b64 v[2:3], 11, v[8:9]
	v_readlane_b32 s12, v245, 37
	v_lshl_add_u64 v[14:15], v[0:1], 0, s[6:7]
	s_lshl_b32 s6, s33, 2
	v_lshl_or_b32 v2, v4, 3, v2
	v_readlane_b32 s24, v245, 49
	v_readlane_b32 s25, v245, 50
	v_lshlrev_b64 v[0:1], 12, v[8:9]
	s_ashr_i32 s7, s6, 31
	v_readlane_b32 s13, v245, 38
	v_lshl_add_u64 v[2:3], s[24:25], 0, v[2:3]
	s_mov_b64 s[10:11], 0x400
	v_lshlrev_b32_e32 v10, 4, v4
	v_lshl_add_u64 v[16:17], s[38:39], 0, v[0:1]
	s_lshl_b64 s[8:9], s[6:7], 12
	v_lshl_add_u64 v[18:19], v[2:3], 0, s[10:11]
	s_lshl_b64 s[10:11], s[6:7], 11
	v_lshl_add_u64 v[20:21], s[40:41], 0, v[0:1]
	s_mov_b64 s[12:13], 0
	v_mov_b32_e32 v9, 0x3727c5ac
	s_mov_b32 s3, 0x800000
	s_movk_i32 s7, 0x3fff
	v_readlane_b32 s14, v245, 39
	v_readlane_b32 s15, v245, 40
	v_readlane_b32 s16, v245, 41
	v_readlane_b32 s17, v245, 42
	v_readlane_b32 s18, v245, 43
	v_readlane_b32 s19, v245, 44
	v_readlane_b32 s20, v245, 45
	v_readlane_b32 s21, v245, 46
	v_readlane_b32 s22, v245, 47
	v_readlane_b32 s23, v245, 48
	v_readlane_b32 s26, v245, 51
	v_readlane_b32 s27, v245, 52
	global_load_dwordx4 v[200:203], v[12:13], off
	global_load_dwordx4 v[216:219], v[14:15], off
	global_load_dwordx4 v[204:207], v[12:13], off offset:1024
	global_load_dwordx4 v[220:223], v[14:15], off offset:1024
	global_load_dwordx4 v[208:211], v[12:13], off offset:2048
	global_load_dwordx4 v[224:227], v[14:15], off offset:2048
	global_load_dwordx4 v[212:215], v[12:13], off offset:3072
	global_load_dwordx4 v[228:231], v[14:15], off offset:3072
